# c24: c16 + nt cache policy on the FFN-in epilogue's HID stores (keep U and the FFN-in weights resident beyond L2 while 180 MB of HID streams out)
# speedup vs baseline: 1.0088x; 1.0088x over previous
.LBB0_347:
	v_exp_f32_e32 v150, v126
	v_exp_f32_e32 v152, v122
	v_exp_f32_e32 v151, v127
	v_exp_f32_e32 v156, v124
	v_exp_f32_e32 v157, v125
	v_exp_f32_e32 v153, v123
	v_exp_f32_e32 v154, v128
	v_exp_f32_e32 v155, v129
	s_lshl_b32 s9, s17, 1
	v_pk_add_f32 v[150:151], v[150:151], 1.0 op_sel_hi:[1,0]
	v_pk_add_f32 v[156:157], v[156:157], 1.0 op_sel_hi:[1,0]
	v_pk_add_f32 v[152:153], v[152:153], 1.0 op_sel_hi:[1,0]
	v_lshl_add_u32 v136, s16, 8, v142
	s_or_b32 s16, s9, s66
	v_rcp_f32_e32 v150, v150
	v_rcp_f32_e32 v152, v152
	v_rcp_f32_e32 v151, v151
	v_rcp_f32_e32 v153, v153
	v_rcp_f32_e32 v156, v156
	v_rcp_f32_e32 v157, v157
	s_ashr_i32 s17, s16, 31
	v_pk_add_f32 v[154:155], v[154:155], 1.0 op_sel_hi:[1,0]
	s_lshl_b64 s[16:17], s[16:17], 14
	v_ashrrev_i32_e32 v137, 31, v136
	v_rcp_f32_e32 v154, v154
	v_rcp_f32_e32 v155, v155
	v_lshl_add_u64 v[148:149], s[16:17], 0, v[136:137]
	v_pk_mul_f32 v[118:119], v[126:127], v[118:119]
	v_pk_mul_f32 v[116:117], v[124:125], v[116:117]
	v_pk_mul_f32 v[114:115], v[122:123], v[114:115]
	v_lshlrev_b64 v[148:149], 7, v[148:149]
	v_pk_mul_f32 v[118:119], v[150:151], v[118:119]
	v_pk_mul_f32 v[122:123], v[156:157], v[116:117]
	v_pk_mul_f32 v[116:117], v[152:153], v[114:115]
	v_lshl_add_u64 v[148:149], v[130:131], 0, v[148:149]
	v_pk_mul_f32 v[120:121], v[128:129], v[120:121]
	v_cvt_pk_bf16_f32 v114, v118, v119
	v_cvt_pk_bf16_f32 v116, v116, v117
	v_cvt_pk_bf16_f32 v117, v122, v123
	v_exp_f32_e32 v118, v106
	v_exp_f32_e32 v122, v108
	v_exp_f32_e32 v123, v109
	v_exp_f32_e32 v119, v107
	v_pk_mul_f32 v[120:121], v[154:155], v[120:121]
	v_pk_mul_f32 v[100:101], v[108:109], v[100:101]
	v_cvt_pk_bf16_f32 v115, v120, v121
	global_store_dwordx4 v[148:149], v[114:117], off nt
	v_exp_f32_e32 v120, v112
	v_exp_f32_e32 v121, v113
	v_exp_f32_e32 v116, v110
	v_exp_f32_e32 v117, v111
	v_pk_add_f32 v[122:123], v[122:123], 1.0 op_sel_hi:[1,0]
	v_pk_add_f32 v[118:119], v[118:119], 1.0 op_sel_hi:[1,0]
	v_rcp_f32_e32 v122, v122
	v_pk_add_f32 v[116:117], v[116:117], 1.0 op_sel_hi:[1,0]
	v_rcp_f32_e32 v118, v118
	v_rcp_f32_e32 v119, v119
	v_rcp_f32_e32 v123, v123
	v_or_b32_e32 v114, 16, v136
	v_pk_add_f32 v[120:121], v[120:121], 1.0 op_sel_hi:[1,0]
	v_rcp_f32_e32 v116, v116
	v_rcp_f32_e32 v117, v117
	v_ashrrev_i32_e32 v115, 31, v114
	v_rcp_f32_e32 v120, v120
	v_rcp_f32_e32 v121, v121
	v_lshl_add_u64 v[114:115], s[16:17], 0, v[114:115]
	v_pk_mul_f32 v[98:99], v[106:107], v[98:99]
	v_lshlrev_b64 v[114:115], 7, v[114:115]
	v_pk_mul_f32 v[102:103], v[110:111], v[102:103]
	v_pk_mul_f32 v[106:107], v[122:123], v[100:101]
	v_pk_mul_f32 v[100:101], v[118:119], v[98:99]
	v_lshl_add_u64 v[114:115], v[130:131], 0, v[114:115]
	v_pk_mul_f32 v[104:105], v[112:113], v[104:105]
	v_pk_mul_f32 v[102:103], v[116:117], v[102:103]
	v_cvt_pk_bf16_f32 v100, v100, v101
	v_cvt_pk_bf16_f32 v101, v106, v107
	v_pk_mul_f32 v[104:105], v[120:121], v[104:105]
	v_cvt_pk_bf16_f32 v98, v102, v103
	v_exp_f32_e32 v102, v90
	v_cvt_pk_bf16_f32 v99, v104, v105
	global_store_dwordx4 v[114:115], v[98:101], off nt
	v_exp_f32_e32 v106, v92
	v_exp_f32_e32 v107, v93
	v_exp_f32_e32 v100, v94
	v_exp_f32_e32 v101, v95
	v_exp_f32_e32 v103, v91
	v_exp_f32_e32 v104, v96
	v_exp_f32_e32 v105, v97
	v_pk_add_f32 v[100:101], v[100:101], 1.0 op_sel_hi:[1,0]
	v_pk_add_f32 v[106:107], v[106:107], 1.0 op_sel_hi:[1,0]
	v_pk_add_f32 v[102:103], v[102:103], 1.0 op_sel_hi:[1,0]
	v_rcp_f32_e32 v100, v100
	v_rcp_f32_e32 v102, v102
	v_rcp_f32_e32 v101, v101
	v_rcp_f32_e32 v103, v103
	v_rcp_f32_e32 v106, v106
	v_rcp_f32_e32 v107, v107
	v_or_b32_e32 v98, 32, v136
	v_pk_add_f32 v[104:105], v[104:105], 1.0 op_sel_hi:[1,0]
	v_ashrrev_i32_e32 v99, 31, v98
	v_rcp_f32_e32 v104, v104
	v_rcp_f32_e32 v105, v105
	v_lshl_add_u64 v[98:99], s[16:17], 0, v[98:99]
	v_pk_mul_f32 v[86:87], v[94:95], v[86:87]
	v_pk_mul_f32 v[84:85], v[92:93], v[84:85]
	v_pk_mul_f32 v[82:83], v[90:91], v[82:83]
	v_lshlrev_b64 v[98:99], 7, v[98:99]
	v_pk_mul_f32 v[86:87], v[100:101], v[86:87]
	v_pk_mul_f32 v[90:91], v[106:107], v[84:85]
	v_pk_mul_f32 v[84:85], v[102:103], v[82:83]
	v_lshl_add_u64 v[98:99], v[130:131], 0, v[98:99]
	v_pk_mul_f32 v[88:89], v[96:97], v[88:89]
	v_cvt_pk_bf16_f32 v82, v86, v87
	v_cvt_pk_bf16_f32 v84, v84, v85
	v_cvt_pk_bf16_f32 v85, v90, v91
	v_exp_f32_e32 v86, v74
	v_exp_f32_e32 v90, v76
	v_exp_f32_e32 v91, v77
	v_exp_f32_e32 v87, v75
	v_pk_mul_f32 v[88:89], v[104:105], v[88:89]
	v_pk_mul_f32 v[68:69], v[76:77], v[68:69]
	v_cvt_pk_bf16_f32 v83, v88, v89
	global_store_dwordx4 v[98:99], v[82:85], off nt
	v_exp_f32_e32 v88, v80
	v_exp_f32_e32 v89, v81
	v_exp_f32_e32 v84, v78
	v_exp_f32_e32 v85, v79
	v_pk_add_f32 v[90:91], v[90:91], 1.0 op_sel_hi:[1,0]
	v_pk_add_f32 v[86:87], v[86:87], 1.0 op_sel_hi:[1,0]
	v_rcp_f32_e32 v90, v90
	v_pk_add_f32 v[84:85], v[84:85], 1.0 op_sel_hi:[1,0]
	v_rcp_f32_e32 v86, v86
	v_rcp_f32_e32 v87, v87
	v_rcp_f32_e32 v91, v91
	v_or_b32_e32 v82, 48, v136
	v_pk_add_f32 v[88:89], v[88:89], 1.0 op_sel_hi:[1,0]
	v_rcp_f32_e32 v84, v84
	v_rcp_f32_e32 v85, v85
	v_ashrrev_i32_e32 v83, 31, v82
	v_rcp_f32_e32 v88, v88
	v_rcp_f32_e32 v89, v89
	v_lshl_add_u64 v[82:83], s[16:17], 0, v[82:83]
	v_pk_mul_f32 v[66:67], v[74:75], v[66:67]
	v_lshlrev_b64 v[82:83], 7, v[82:83]
	v_pk_mul_f32 v[70:71], v[78:79], v[70:71]
	v_pk_mul_f32 v[74:75], v[90:91], v[68:69]
	v_pk_mul_f32 v[68:69], v[86:87], v[66:67]
	v_lshl_add_u64 v[82:83], v[130:131], 0, v[82:83]
	v_pk_mul_f32 v[72:73], v[80:81], v[72:73]
	v_pk_mul_f32 v[70:71], v[84:85], v[70:71]
	v_cvt_pk_bf16_f32 v68, v68, v69
	v_cvt_pk_bf16_f32 v69, v74, v75
	v_pk_mul_f32 v[72:73], v[88:89], v[72:73]
	v_cvt_pk_bf16_f32 v66, v70, v71
	v_exp_f32_e32 v70, v58
	v_cvt_pk_bf16_f32 v67, v72, v73
	global_store_dwordx4 v[82:83], v[66:69], off nt
	v_exp_f32_e32 v74, v60
	v_exp_f32_e32 v75, v61
	v_exp_f32_e32 v68, v62
	v_exp_f32_e32 v69, v63
	v_exp_f32_e32 v71, v59
	v_exp_f32_e32 v72, v64
	v_exp_f32_e32 v73, v65
	v_pk_add_f32 v[68:69], v[68:69], 1.0 op_sel_hi:[1,0]
	v_pk_add_f32 v[74:75], v[74:75], 1.0 op_sel_hi:[1,0]
	v_pk_add_f32 v[70:71], v[70:71], 1.0 op_sel_hi:[1,0]
	v_rcp_f32_e32 v68, v68
	v_rcp_f32_e32 v70, v70
	v_rcp_f32_e32 v69, v69
	v_rcp_f32_e32 v71, v71
	v_rcp_f32_e32 v74, v74
	v_rcp_f32_e32 v75, v75
	v_add_u32_e32 v66, 0x80, v136
	v_pk_add_f32 v[72:73], v[72:73], 1.0 op_sel_hi:[1,0]
	v_ashrrev_i32_e32 v67, 31, v66
	v_rcp_f32_e32 v72, v72
	v_rcp_f32_e32 v73, v73
	v_lshl_add_u64 v[66:67], s[16:17], 0, v[66:67]
	v_pk_mul_f32 v[54:55], v[62:63], v[54:55]
	v_pk_mul_f32 v[52:53], v[60:61], v[52:53]
	v_pk_mul_f32 v[50:51], v[58:59], v[50:51]
	v_lshlrev_b64 v[66:67], 7, v[66:67]
	v_pk_mul_f32 v[54:55], v[68:69], v[54:55]
	v_pk_mul_f32 v[58:59], v[74:75], v[52:53]
	v_pk_mul_f32 v[52:53], v[70:71], v[50:51]
	v_lshl_add_u64 v[66:67], v[130:131], 0, v[66:67]
	v_pk_mul_f32 v[56:57], v[64:65], v[56:57]
	v_cvt_pk_bf16_f32 v50, v54, v55
	v_cvt_pk_bf16_f32 v52, v52, v53
	v_cvt_pk_bf16_f32 v53, v58, v59
	v_exp_f32_e32 v54, v42
	v_exp_f32_e32 v58, v44
	v_exp_f32_e32 v59, v45
	v_exp_f32_e32 v55, v43
	v_pk_mul_f32 v[56:57], v[72:73], v[56:57]
	v_pk_mul_f32 v[36:37], v[44:45], v[36:37]
	v_cvt_pk_bf16_f32 v51, v56, v57
	global_store_dwordx4 v[66:67], v[50:53], off nt
	v_exp_f32_e32 v56, v48
	v_exp_f32_e32 v57, v49
	v_exp_f32_e32 v52, v46
	v_exp_f32_e32 v53, v47
	v_pk_add_f32 v[58:59], v[58:59], 1.0 op_sel_hi:[1,0]
	v_pk_add_f32 v[54:55], v[54:55], 1.0 op_sel_hi:[1,0]
	v_rcp_f32_e32 v58, v58
	v_pk_add_f32 v[52:53], v[52:53], 1.0 op_sel_hi:[1,0]
	v_rcp_f32_e32 v54, v54
	v_rcp_f32_e32 v55, v55
	v_rcp_f32_e32 v59, v59
	v_add_u32_e32 v50, 0x90, v136
	v_pk_add_f32 v[56:57], v[56:57], 1.0 op_sel_hi:[1,0]
	v_rcp_f32_e32 v52, v52
	v_rcp_f32_e32 v53, v53
	v_ashrrev_i32_e32 v51, 31, v50
	v_rcp_f32_e32 v56, v56
	v_rcp_f32_e32 v57, v57
	v_lshl_add_u64 v[50:51], s[16:17], 0, v[50:51]
	v_pk_mul_f32 v[34:35], v[42:43], v[34:35]
	v_lshlrev_b64 v[50:51], 7, v[50:51]
	v_pk_mul_f32 v[38:39], v[46:47], v[38:39]
	v_pk_mul_f32 v[42:43], v[58:59], v[36:37]
	v_pk_mul_f32 v[36:37], v[54:55], v[34:35]
	v_lshl_add_u64 v[50:51], v[130:131], 0, v[50:51]
	v_pk_mul_f32 v[40:41], v[48:49], v[40:41]
	v_pk_mul_f32 v[38:39], v[52:53], v[38:39]
	v_cvt_pk_bf16_f32 v36, v36, v37
	v_cvt_pk_bf16_f32 v37, v42, v43
	v_pk_mul_f32 v[40:41], v[56:57], v[40:41]
	v_cvt_pk_bf16_f32 v34, v38, v39
	v_exp_f32_e32 v38, v26
	v_cvt_pk_bf16_f32 v35, v40, v41
	global_store_dwordx4 v[50:51], v[34:37], off nt
	v_exp_f32_e32 v42, v28
	v_exp_f32_e32 v43, v29
	v_exp_f32_e32 v36, v30
	v_exp_f32_e32 v37, v31
	v_exp_f32_e32 v39, v27
	v_exp_f32_e32 v40, v32
	v_exp_f32_e32 v41, v33
	v_pk_add_f32 v[36:37], v[36:37], 1.0 op_sel_hi:[1,0]
	v_pk_add_f32 v[42:43], v[42:43], 1.0 op_sel_hi:[1,0]
	v_pk_add_f32 v[38:39], v[38:39], 1.0 op_sel_hi:[1,0]
	v_pk_add_f32 v[40:41], v[40:41], 1.0 op_sel_hi:[1,0]
	v_rcp_f32_e32 v36, v36
	v_rcp_f32_e32 v38, v38
	v_rcp_f32_e32 v37, v37
	v_rcp_f32_e32 v39, v39
	v_rcp_f32_e32 v42, v42
	v_rcp_f32_e32 v43, v43
	v_add_u32_e32 v34, 0xa0, v136
	v_rcp_f32_e32 v40, v40
	v_rcp_f32_e32 v41, v41
	v_ashrrev_i32_e32 v35, 31, v34
	v_lshl_add_u64 v[34:35], s[16:17], 0, v[34:35]
	v_pk_mul_f32 v[22:23], v[30:31], v[22:23]
	v_pk_mul_f32 v[20:21], v[28:29], v[20:21]
	v_pk_mul_f32 v[18:19], v[26:27], v[18:19]
	v_lshlrev_b64 v[34:35], 7, v[34:35]
	v_pk_mul_f32 v[24:25], v[32:33], v[24:25]
	v_pk_mul_f32 v[22:23], v[36:37], v[22:23]
	v_pk_mul_f32 v[26:27], v[42:43], v[20:21]
	v_pk_mul_f32 v[20:21], v[38:39], v[18:19]
	v_lshl_add_u64 v[34:35], v[130:131], 0, v[34:35]
	v_pk_mul_f32 v[24:25], v[40:41], v[24:25]
	v_cvt_pk_bf16_f32 v18, v22, v23
	v_cvt_pk_bf16_f32 v20, v20, v21
	v_cvt_pk_bf16_f32 v21, v26, v27
	v_exp_f32_e32 v22, v10
	v_exp_f32_e32 v26, v12
	v_exp_f32_e32 v27, v13
	v_exp_f32_e32 v23, v11
	v_cvt_pk_bf16_f32 v19, v24, v25
	global_store_dwordx4 v[34:35], v[18:21], off nt
	v_exp_f32_e32 v24, v16
	v_exp_f32_e32 v25, v17
	v_exp_f32_e32 v20, v14
	v_exp_f32_e32 v21, v15
	v_pk_add_f32 v[26:27], v[26:27], 1.0 op_sel_hi:[1,0]
	v_pk_add_f32 v[22:23], v[22:23], 1.0 op_sel_hi:[1,0]
	v_add_u32_e32 v18, 0xb0, v136
	v_pk_add_f32 v[24:25], v[24:25], 1.0 op_sel_hi:[1,0]
	v_pk_add_f32 v[20:21], v[20:21], 1.0 op_sel_hi:[1,0]
	v_rcp_f32_e32 v22, v22
	v_rcp_f32_e32 v23, v23
	v_rcp_f32_e32 v26, v26
	v_rcp_f32_e32 v27, v27
	v_ashrrev_i32_e32 v19, 31, v18
	v_rcp_f32_e32 v20, v20
	v_rcp_f32_e32 v21, v21
	v_rcp_f32_e32 v24, v24
	v_rcp_f32_e32 v25, v25
	v_lshl_add_u64 v[18:19], s[16:17], 0, v[18:19]
	v_lshlrev_b64 v[18:19], 7, v[18:19]
	v_pk_mul_f32 v[4:5], v[12:13], v[4:5]
	v_pk_mul_f32 v[2:3], v[10:11], v[2:3]
	v_lshl_add_u64 v[18:19], v[130:131], 0, v[18:19]
	v_pk_mul_f32 v[8:9], v[16:17], v[8:9]
	v_pk_mul_f32 v[6:7], v[14:15], v[6:7]
	v_pk_mul_f32 v[10:11], v[26:27], v[4:5]
	v_pk_mul_f32 v[4:5], v[22:23], v[2:3]
	s_andn2_b64 vcc, exec, s[2:3]
	s_mov_b64 s[2:3], -1
	v_pk_mul_f32 v[8:9], v[24:25], v[8:9]
	v_pk_mul_f32 v[6:7], v[20:21], v[6:7]
	v_cvt_pk_bf16_f32 v3, v8, v9
	v_cvt_pk_bf16_f32 v4, v4, v5
	v_cvt_pk_bf16_f32 v5, v10, v11
	s_nop 0
	v_cvt_pk_bf16_f32 v2, v6, v7
	global_store_dwordx4 v[18:19], v[2:5], off nt
	s_cbranch_vccnz .LBB0_340
	s_andn2_b64 vcc, exec, s[4:5]
	s_cbranch_vccnz .LBB0_339
	s_barrier
	s_branch .LBB0_339

.LBB0_1227:
	v_exp_f32_e32 v150, v126
	v_exp_f32_e32 v152, v122
	v_exp_f32_e32 v151, v127
	v_exp_f32_e32 v156, v124
	v_exp_f32_e32 v157, v125
	v_exp_f32_e32 v153, v123
	v_exp_f32_e32 v154, v128
	v_exp_f32_e32 v155, v129
	s_lshl_b32 s9, s17, 1
	v_pk_add_f32 v[150:151], v[150:151], 1.0 op_sel_hi:[1,0]
	v_pk_add_f32 v[156:157], v[156:157], 1.0 op_sel_hi:[1,0]
	v_pk_add_f32 v[152:153], v[152:153], 1.0 op_sel_hi:[1,0]
	v_lshl_add_u32 v136, s16, 8, v142
	s_or_b32 s16, s9, s58
	v_rcp_f32_e32 v150, v150
	v_rcp_f32_e32 v152, v152
	v_rcp_f32_e32 v151, v151
	v_rcp_f32_e32 v153, v153
	v_rcp_f32_e32 v156, v156
	v_rcp_f32_e32 v157, v157
	s_ashr_i32 s17, s16, 31
	v_pk_add_f32 v[154:155], v[154:155], 1.0 op_sel_hi:[1,0]
	s_lshl_b64 s[16:17], s[16:17], 14
	v_ashrrev_i32_e32 v137, 31, v136
	v_rcp_f32_e32 v154, v154
	v_rcp_f32_e32 v155, v155
	v_lshl_add_u64 v[148:149], s[16:17], 0, v[136:137]
	v_pk_mul_f32 v[118:119], v[126:127], v[118:119]
	v_pk_mul_f32 v[116:117], v[124:125], v[116:117]
	v_pk_mul_f32 v[114:115], v[122:123], v[114:115]
	v_lshlrev_b64 v[148:149], 7, v[148:149]
	v_pk_mul_f32 v[118:119], v[150:151], v[118:119]
	v_pk_mul_f32 v[122:123], v[156:157], v[116:117]
	v_pk_mul_f32 v[116:117], v[152:153], v[114:115]
	v_lshl_add_u64 v[148:149], v[130:131], 0, v[148:149]
	v_pk_mul_f32 v[120:121], v[128:129], v[120:121]
	v_cvt_pk_bf16_f32 v114, v118, v119
	v_cvt_pk_bf16_f32 v116, v116, v117
	v_cvt_pk_bf16_f32 v117, v122, v123
	v_exp_f32_e32 v118, v106
	v_exp_f32_e32 v122, v108
	v_exp_f32_e32 v123, v109
	v_exp_f32_e32 v119, v107
	v_pk_mul_f32 v[120:121], v[154:155], v[120:121]
	v_pk_mul_f32 v[100:101], v[108:109], v[100:101]
	v_cvt_pk_bf16_f32 v115, v120, v121
	global_store_dwordx4 v[148:149], v[114:117], off nt
	v_exp_f32_e32 v120, v112
	v_exp_f32_e32 v121, v113
	v_exp_f32_e32 v116, v110
	v_exp_f32_e32 v117, v111
	v_pk_add_f32 v[122:123], v[122:123], 1.0 op_sel_hi:[1,0]
	v_pk_add_f32 v[118:119], v[118:119], 1.0 op_sel_hi:[1,0]
	v_rcp_f32_e32 v122, v122
	v_pk_add_f32 v[116:117], v[116:117], 1.0 op_sel_hi:[1,0]
	v_rcp_f32_e32 v118, v118
	v_rcp_f32_e32 v119, v119
	v_rcp_f32_e32 v123, v123
	v_or_b32_e32 v114, 16, v136
	v_pk_add_f32 v[120:121], v[120:121], 1.0 op_sel_hi:[1,0]
	v_rcp_f32_e32 v116, v116
	v_rcp_f32_e32 v117, v117
	v_ashrrev_i32_e32 v115, 31, v114
	v_rcp_f32_e32 v120, v120
	v_rcp_f32_e32 v121, v121
	v_lshl_add_u64 v[114:115], s[16:17], 0, v[114:115]
	v_pk_mul_f32 v[98:99], v[106:107], v[98:99]
	v_lshlrev_b64 v[114:115], 7, v[114:115]
	v_pk_mul_f32 v[102:103], v[110:111], v[102:103]
	v_pk_mul_f32 v[106:107], v[122:123], v[100:101]
	v_pk_mul_f32 v[100:101], v[118:119], v[98:99]
	v_lshl_add_u64 v[114:115], v[130:131], 0, v[114:115]
	v_pk_mul_f32 v[104:105], v[112:113], v[104:105]
	v_pk_mul_f32 v[102:103], v[116:117], v[102:103]
	v_cvt_pk_bf16_f32 v100, v100, v101
	v_cvt_pk_bf16_f32 v101, v106, v107
	v_pk_mul_f32 v[104:105], v[120:121], v[104:105]
	v_cvt_pk_bf16_f32 v98, v102, v103
	v_exp_f32_e32 v102, v90
	v_cvt_pk_bf16_f32 v99, v104, v105
	global_store_dwordx4 v[114:115], v[98:101], off nt
	v_exp_f32_e32 v106, v92
	v_exp_f32_e32 v107, v93
	v_exp_f32_e32 v100, v94
	v_exp_f32_e32 v101, v95
	v_exp_f32_e32 v103, v91
	v_exp_f32_e32 v104, v96
	v_exp_f32_e32 v105, v97
	v_pk_add_f32 v[100:101], v[100:101], 1.0 op_sel_hi:[1,0]
	v_pk_add_f32 v[106:107], v[106:107], 1.0 op_sel_hi:[1,0]
	v_pk_add_f32 v[102:103], v[102:103], 1.0 op_sel_hi:[1,0]
	v_rcp_f32_e32 v100, v100
	v_rcp_f32_e32 v102, v102
	v_rcp_f32_e32 v101, v101
	v_rcp_f32_e32 v103, v103
	v_rcp_f32_e32 v106, v106
	v_rcp_f32_e32 v107, v107
	v_or_b32_e32 v98, 32, v136
	v_pk_add_f32 v[104:105], v[104:105], 1.0 op_sel_hi:[1,0]
	v_ashrrev_i32_e32 v99, 31, v98
	v_rcp_f32_e32 v104, v104
	v_rcp_f32_e32 v105, v105
	v_lshl_add_u64 v[98:99], s[16:17], 0, v[98:99]
	v_pk_mul_f32 v[86:87], v[94:95], v[86:87]
	v_pk_mul_f32 v[84:85], v[92:93], v[84:85]
	v_pk_mul_f32 v[82:83], v[90:91], v[82:83]
	v_lshlrev_b64 v[98:99], 7, v[98:99]
	v_pk_mul_f32 v[86:87], v[100:101], v[86:87]
	v_pk_mul_f32 v[90:91], v[106:107], v[84:85]
	v_pk_mul_f32 v[84:85], v[102:103], v[82:83]
	v_lshl_add_u64 v[98:99], v[130:131], 0, v[98:99]
	v_pk_mul_f32 v[88:89], v[96:97], v[88:89]
	v_cvt_pk_bf16_f32 v82, v86, v87
	v_cvt_pk_bf16_f32 v84, v84, v85
	v_cvt_pk_bf16_f32 v85, v90, v91
	v_exp_f32_e32 v86, v74
	v_exp_f32_e32 v90, v76
	v_exp_f32_e32 v91, v77
	v_exp_f32_e32 v87, v75
	v_pk_mul_f32 v[88:89], v[104:105], v[88:89]
	v_pk_mul_f32 v[68:69], v[76:77], v[68:69]
	v_cvt_pk_bf16_f32 v83, v88, v89
	global_store_dwordx4 v[98:99], v[82:85], off nt
	v_exp_f32_e32 v88, v80
	v_exp_f32_e32 v89, v81
	v_exp_f32_e32 v84, v78
	v_exp_f32_e32 v85, v79
	v_pk_add_f32 v[90:91], v[90:91], 1.0 op_sel_hi:[1,0]
	v_pk_add_f32 v[86:87], v[86:87], 1.0 op_sel_hi:[1,0]
	v_rcp_f32_e32 v90, v90
	v_pk_add_f32 v[84:85], v[84:85], 1.0 op_sel_hi:[1,0]
	v_rcp_f32_e32 v86, v86
	v_rcp_f32_e32 v87, v87
	v_rcp_f32_e32 v91, v91
	v_or_b32_e32 v82, 48, v136
	v_pk_add_f32 v[88:89], v[88:89], 1.0 op_sel_hi:[1,0]
	v_rcp_f32_e32 v84, v84
	v_rcp_f32_e32 v85, v85
	v_ashrrev_i32_e32 v83, 31, v82
	v_rcp_f32_e32 v88, v88
	v_rcp_f32_e32 v89, v89
	v_lshl_add_u64 v[82:83], s[16:17], 0, v[82:83]
	v_pk_mul_f32 v[66:67], v[74:75], v[66:67]
	v_lshlrev_b64 v[82:83], 7, v[82:83]
	v_pk_mul_f32 v[70:71], v[78:79], v[70:71]
	v_pk_mul_f32 v[74:75], v[90:91], v[68:69]
	v_pk_mul_f32 v[68:69], v[86:87], v[66:67]
	v_lshl_add_u64 v[82:83], v[130:131], 0, v[82:83]
	v_pk_mul_f32 v[72:73], v[80:81], v[72:73]
	v_pk_mul_f32 v[70:71], v[84:85], v[70:71]
	v_cvt_pk_bf16_f32 v68, v68, v69
	v_cvt_pk_bf16_f32 v69, v74, v75
	v_pk_mul_f32 v[72:73], v[88:89], v[72:73]
	v_cvt_pk_bf16_f32 v66, v70, v71
	v_exp_f32_e32 v70, v58
	v_cvt_pk_bf16_f32 v67, v72, v73
	global_store_dwordx4 v[82:83], v[66:69], off nt
	v_exp_f32_e32 v74, v60
	v_exp_f32_e32 v75, v61
	v_exp_f32_e32 v68, v62
	v_exp_f32_e32 v69, v63
	v_exp_f32_e32 v71, v59
	v_exp_f32_e32 v72, v64
	v_exp_f32_e32 v73, v65
	v_pk_add_f32 v[68:69], v[68:69], 1.0 op_sel_hi:[1,0]
	v_pk_add_f32 v[74:75], v[74:75], 1.0 op_sel_hi:[1,0]
	v_pk_add_f32 v[70:71], v[70:71], 1.0 op_sel_hi:[1,0]
	v_rcp_f32_e32 v68, v68
	v_rcp_f32_e32 v70, v70
	v_rcp_f32_e32 v69, v69
	v_rcp_f32_e32 v71, v71
	v_rcp_f32_e32 v74, v74
	v_rcp_f32_e32 v75, v75
	v_add_u32_e32 v66, 0x80, v136
	v_pk_add_f32 v[72:73], v[72:73], 1.0 op_sel_hi:[1,0]
	v_ashrrev_i32_e32 v67, 31, v66
	v_rcp_f32_e32 v72, v72
	v_rcp_f32_e32 v73, v73
	v_lshl_add_u64 v[66:67], s[16:17], 0, v[66:67]
	v_pk_mul_f32 v[54:55], v[62:63], v[54:55]
	v_pk_mul_f32 v[52:53], v[60:61], v[52:53]
	v_pk_mul_f32 v[50:51], v[58:59], v[50:51]
	v_lshlrev_b64 v[66:67], 7, v[66:67]
	v_pk_mul_f32 v[54:55], v[68:69], v[54:55]
	v_pk_mul_f32 v[58:59], v[74:75], v[52:53]
	v_pk_mul_f32 v[52:53], v[70:71], v[50:51]
	v_lshl_add_u64 v[66:67], v[130:131], 0, v[66:67]
	v_pk_mul_f32 v[56:57], v[64:65], v[56:57]
	v_cvt_pk_bf16_f32 v50, v54, v55
	v_cvt_pk_bf16_f32 v52, v52, v53
	v_cvt_pk_bf16_f32 v53, v58, v59
	v_exp_f32_e32 v54, v42
	v_exp_f32_e32 v58, v44
	v_exp_f32_e32 v59, v45
	v_exp_f32_e32 v55, v43
	v_pk_mul_f32 v[56:57], v[72:73], v[56:57]
	v_pk_mul_f32 v[36:37], v[44:45], v[36:37]
	v_cvt_pk_bf16_f32 v51, v56, v57
	global_store_dwordx4 v[66:67], v[50:53], off nt
	v_exp_f32_e32 v56, v48
	v_exp_f32_e32 v57, v49
	v_exp_f32_e32 v52, v46
	v_exp_f32_e32 v53, v47
	v_pk_add_f32 v[58:59], v[58:59], 1.0 op_sel_hi:[1,0]
	v_pk_add_f32 v[54:55], v[54:55], 1.0 op_sel_hi:[1,0]
	v_rcp_f32_e32 v58, v58
	v_pk_add_f32 v[52:53], v[52:53], 1.0 op_sel_hi:[1,0]
	v_rcp_f32_e32 v54, v54
	v_rcp_f32_e32 v55, v55
	v_rcp_f32_e32 v59, v59
	v_add_u32_e32 v50, 0x90, v136
	v_pk_add_f32 v[56:57], v[56:57], 1.0 op_sel_hi:[1,0]
	v_rcp_f32_e32 v52, v52
	v_rcp_f32_e32 v53, v53
	v_ashrrev_i32_e32 v51, 31, v50
	v_rcp_f32_e32 v56, v56
	v_rcp_f32_e32 v57, v57
	v_lshl_add_u64 v[50:51], s[16:17], 0, v[50:51]
	v_pk_mul_f32 v[34:35], v[42:43], v[34:35]
	v_lshlrev_b64 v[50:51], 7, v[50:51]
	v_pk_mul_f32 v[38:39], v[46:47], v[38:39]
	v_pk_mul_f32 v[42:43], v[58:59], v[36:37]
	v_pk_mul_f32 v[36:37], v[54:55], v[34:35]
	v_lshl_add_u64 v[50:51], v[130:131], 0, v[50:51]
	v_pk_mul_f32 v[40:41], v[48:49], v[40:41]
	v_pk_mul_f32 v[38:39], v[52:53], v[38:39]
	v_cvt_pk_bf16_f32 v36, v36, v37
	v_cvt_pk_bf16_f32 v37, v42, v43
	v_pk_mul_f32 v[40:41], v[56:57], v[40:41]
	v_cvt_pk_bf16_f32 v34, v38, v39
	v_exp_f32_e32 v38, v26
	v_cvt_pk_bf16_f32 v35, v40, v41
	global_store_dwordx4 v[50:51], v[34:37], off nt
	v_exp_f32_e32 v42, v28
	v_exp_f32_e32 v43, v29
	v_exp_f32_e32 v36, v30
	v_exp_f32_e32 v37, v31
	v_exp_f32_e32 v39, v27
	v_exp_f32_e32 v40, v32
	v_exp_f32_e32 v41, v33
	v_pk_add_f32 v[36:37], v[36:37], 1.0 op_sel_hi:[1,0]
	v_pk_add_f32 v[42:43], v[42:43], 1.0 op_sel_hi:[1,0]
	v_pk_add_f32 v[38:39], v[38:39], 1.0 op_sel_hi:[1,0]
	v_pk_add_f32 v[40:41], v[40:41], 1.0 op_sel_hi:[1,0]
	v_rcp_f32_e32 v36, v36
	v_rcp_f32_e32 v38, v38
	v_rcp_f32_e32 v37, v37
	v_rcp_f32_e32 v39, v39
	v_rcp_f32_e32 v42, v42
	v_rcp_f32_e32 v43, v43
	v_add_u32_e32 v34, 0xa0, v136
	v_rcp_f32_e32 v40, v40
	v_rcp_f32_e32 v41, v41
	v_ashrrev_i32_e32 v35, 31, v34
	v_lshl_add_u64 v[34:35], s[16:17], 0, v[34:35]
	v_pk_mul_f32 v[22:23], v[30:31], v[22:23]
	v_pk_mul_f32 v[20:21], v[28:29], v[20:21]
	v_pk_mul_f32 v[18:19], v[26:27], v[18:19]
	v_lshlrev_b64 v[34:35], 7, v[34:35]
	v_pk_mul_f32 v[24:25], v[32:33], v[24:25]
	v_pk_mul_f32 v[22:23], v[36:37], v[22:23]
	v_pk_mul_f32 v[26:27], v[42:43], v[20:21]
	v_pk_mul_f32 v[20:21], v[38:39], v[18:19]
	v_lshl_add_u64 v[34:35], v[130:131], 0, v[34:35]
	v_pk_mul_f32 v[24:25], v[40:41], v[24:25]
	v_cvt_pk_bf16_f32 v18, v22, v23
	v_cvt_pk_bf16_f32 v20, v20, v21
	v_cvt_pk_bf16_f32 v21, v26, v27
	v_exp_f32_e32 v22, v10
	v_exp_f32_e32 v26, v12
	v_exp_f32_e32 v27, v13
	v_exp_f32_e32 v23, v11
	v_cvt_pk_bf16_f32 v19, v24, v25
	global_store_dwordx4 v[34:35], v[18:21], off nt
	v_exp_f32_e32 v24, v16
	v_exp_f32_e32 v25, v17
	v_exp_f32_e32 v20, v14
	v_exp_f32_e32 v21, v15
	v_pk_add_f32 v[26:27], v[26:27], 1.0 op_sel_hi:[1,0]
	v_pk_add_f32 v[22:23], v[22:23], 1.0 op_sel_hi:[1,0]
	v_add_u32_e32 v18, 0xb0, v136
	v_pk_add_f32 v[24:25], v[24:25], 1.0 op_sel_hi:[1,0]
	v_pk_add_f32 v[20:21], v[20:21], 1.0 op_sel_hi:[1,0]
	v_rcp_f32_e32 v22, v22
	v_rcp_f32_e32 v23, v23
	v_rcp_f32_e32 v26, v26
	v_rcp_f32_e32 v27, v27
	v_ashrrev_i32_e32 v19, 31, v18
	v_rcp_f32_e32 v20, v20
	v_rcp_f32_e32 v21, v21
	v_rcp_f32_e32 v24, v24
	v_rcp_f32_e32 v25, v25
	v_lshl_add_u64 v[18:19], s[16:17], 0, v[18:19]
	v_lshlrev_b64 v[18:19], 7, v[18:19]
	v_pk_mul_f32 v[4:5], v[12:13], v[4:5]
	v_pk_mul_f32 v[2:3], v[10:11], v[2:3]
	v_lshl_add_u64 v[18:19], v[130:131], 0, v[18:19]
	v_pk_mul_f32 v[8:9], v[16:17], v[8:9]
	v_pk_mul_f32 v[6:7], v[14:15], v[6:7]
	v_pk_mul_f32 v[10:11], v[26:27], v[4:5]
	v_pk_mul_f32 v[4:5], v[22:23], v[2:3]
	s_andn2_b64 vcc, exec, s[2:3]
	s_mov_b64 s[2:3], -1
	v_pk_mul_f32 v[8:9], v[24:25], v[8:9]
	v_pk_mul_f32 v[6:7], v[20:21], v[6:7]
	v_cvt_pk_bf16_f32 v3, v8, v9
	v_cvt_pk_bf16_f32 v4, v4, v5
	v_cvt_pk_bf16_f32 v5, v10, v11
	s_nop 0
	v_cvt_pk_bf16_f32 v2, v6, v7
	global_store_dwordx4 v[18:19], v[2:5], off nt
	s_cbranch_vccnz .LBB0_1220
	s_andn2_b64 vcc, exec, s[4:5]
	s_cbranch_vccnz .LBB0_1219
	s_barrier
	s_branch .LBB0_1219

.LBB0_2597:
	v_exp_f32_e32 v150, v126
	v_exp_f32_e32 v152, v122
	v_exp_f32_e32 v151, v127
	v_exp_f32_e32 v156, v124
	v_exp_f32_e32 v157, v125
	v_exp_f32_e32 v153, v123
	v_exp_f32_e32 v154, v128
	v_exp_f32_e32 v155, v129
	s_lshl_b32 s9, s17, 1
	v_pk_add_f32 v[150:151], v[150:151], 1.0 op_sel_hi:[1,0]
	v_pk_add_f32 v[156:157], v[156:157], 1.0 op_sel_hi:[1,0]
	v_pk_add_f32 v[152:153], v[152:153], 1.0 op_sel_hi:[1,0]
	v_lshl_add_u32 v136, s16, 8, v142
	s_or_b32 s16, s9, s56
	v_rcp_f32_e32 v150, v150
	v_rcp_f32_e32 v152, v152
	v_rcp_f32_e32 v151, v151
	v_rcp_f32_e32 v153, v153
	v_rcp_f32_e32 v156, v156
	v_rcp_f32_e32 v157, v157
	s_ashr_i32 s17, s16, 31
	v_pk_add_f32 v[154:155], v[154:155], 1.0 op_sel_hi:[1,0]
	s_lshl_b64 s[16:17], s[16:17], 14
	v_ashrrev_i32_e32 v137, 31, v136
	v_rcp_f32_e32 v154, v154
	v_rcp_f32_e32 v155, v155
	v_lshl_add_u64 v[148:149], s[16:17], 0, v[136:137]
	v_pk_mul_f32 v[118:119], v[126:127], v[118:119]
	v_pk_mul_f32 v[116:117], v[124:125], v[116:117]
	v_pk_mul_f32 v[114:115], v[122:123], v[114:115]
	v_lshlrev_b64 v[148:149], 7, v[148:149]
	v_pk_mul_f32 v[118:119], v[150:151], v[118:119]
	v_pk_mul_f32 v[122:123], v[156:157], v[116:117]
	v_pk_mul_f32 v[116:117], v[152:153], v[114:115]
	v_lshl_add_u64 v[148:149], v[130:131], 0, v[148:149]
	v_pk_mul_f32 v[120:121], v[128:129], v[120:121]
	v_cvt_pk_bf16_f32 v114, v118, v119
	v_cvt_pk_bf16_f32 v116, v116, v117
	v_cvt_pk_bf16_f32 v117, v122, v123
	v_exp_f32_e32 v118, v106
	v_exp_f32_e32 v122, v108
	v_exp_f32_e32 v123, v109
	v_exp_f32_e32 v119, v107
	v_pk_mul_f32 v[120:121], v[154:155], v[120:121]
	v_pk_mul_f32 v[100:101], v[108:109], v[100:101]
	v_cvt_pk_bf16_f32 v115, v120, v121
	global_store_dwordx4 v[148:149], v[114:117], off nt
	v_exp_f32_e32 v120, v112
	v_exp_f32_e32 v121, v113
	v_exp_f32_e32 v116, v110
	v_exp_f32_e32 v117, v111
	v_pk_add_f32 v[122:123], v[122:123], 1.0 op_sel_hi:[1,0]
	v_pk_add_f32 v[118:119], v[118:119], 1.0 op_sel_hi:[1,0]
	v_rcp_f32_e32 v122, v122
	v_pk_add_f32 v[116:117], v[116:117], 1.0 op_sel_hi:[1,0]
	v_rcp_f32_e32 v118, v118
	v_rcp_f32_e32 v119, v119
	v_rcp_f32_e32 v123, v123
	v_or_b32_e32 v114, 16, v136
	v_pk_add_f32 v[120:121], v[120:121], 1.0 op_sel_hi:[1,0]
	v_rcp_f32_e32 v116, v116
	v_rcp_f32_e32 v117, v117
	v_ashrrev_i32_e32 v115, 31, v114
	v_rcp_f32_e32 v120, v120
	v_rcp_f32_e32 v121, v121
	v_lshl_add_u64 v[114:115], s[16:17], 0, v[114:115]
	v_pk_mul_f32 v[98:99], v[106:107], v[98:99]
	v_lshlrev_b64 v[114:115], 7, v[114:115]
	v_pk_mul_f32 v[102:103], v[110:111], v[102:103]
	v_pk_mul_f32 v[106:107], v[122:123], v[100:101]
	v_pk_mul_f32 v[100:101], v[118:119], v[98:99]
	v_lshl_add_u64 v[114:115], v[130:131], 0, v[114:115]
	v_pk_mul_f32 v[104:105], v[112:113], v[104:105]
	v_pk_mul_f32 v[102:103], v[116:117], v[102:103]
	v_cvt_pk_bf16_f32 v100, v100, v101
	v_cvt_pk_bf16_f32 v101, v106, v107
	v_pk_mul_f32 v[104:105], v[120:121], v[104:105]
	v_cvt_pk_bf16_f32 v98, v102, v103
	v_exp_f32_e32 v102, v90
	v_cvt_pk_bf16_f32 v99, v104, v105
	global_store_dwordx4 v[114:115], v[98:101], off nt
	v_exp_f32_e32 v106, v92
	v_exp_f32_e32 v107, v93
	v_exp_f32_e32 v100, v94
	v_exp_f32_e32 v101, v95
	v_exp_f32_e32 v103, v91
	v_exp_f32_e32 v104, v96
	v_exp_f32_e32 v105, v97
	v_pk_add_f32 v[100:101], v[100:101], 1.0 op_sel_hi:[1,0]
	v_pk_add_f32 v[106:107], v[106:107], 1.0 op_sel_hi:[1,0]
	v_pk_add_f32 v[102:103], v[102:103], 1.0 op_sel_hi:[1,0]
	v_rcp_f32_e32 v100, v100
	v_rcp_f32_e32 v102, v102
	v_rcp_f32_e32 v101, v101
	v_rcp_f32_e32 v103, v103
	v_rcp_f32_e32 v106, v106
	v_rcp_f32_e32 v107, v107
	v_or_b32_e32 v98, 32, v136
	v_pk_add_f32 v[104:105], v[104:105], 1.0 op_sel_hi:[1,0]
	v_ashrrev_i32_e32 v99, 31, v98
	v_rcp_f32_e32 v104, v104
	v_rcp_f32_e32 v105, v105
	v_lshl_add_u64 v[98:99], s[16:17], 0, v[98:99]
	v_pk_mul_f32 v[86:87], v[94:95], v[86:87]
	v_pk_mul_f32 v[84:85], v[92:93], v[84:85]
	v_pk_mul_f32 v[82:83], v[90:91], v[82:83]
	v_lshlrev_b64 v[98:99], 7, v[98:99]
	v_pk_mul_f32 v[86:87], v[100:101], v[86:87]
	v_pk_mul_f32 v[90:91], v[106:107], v[84:85]
	v_pk_mul_f32 v[84:85], v[102:103], v[82:83]
	v_lshl_add_u64 v[98:99], v[130:131], 0, v[98:99]
	v_pk_mul_f32 v[88:89], v[96:97], v[88:89]
	v_cvt_pk_bf16_f32 v82, v86, v87
	v_cvt_pk_bf16_f32 v84, v84, v85
	v_cvt_pk_bf16_f32 v85, v90, v91
	v_exp_f32_e32 v86, v74
	v_exp_f32_e32 v90, v76
	v_exp_f32_e32 v91, v77
	v_exp_f32_e32 v87, v75
	v_pk_mul_f32 v[88:89], v[104:105], v[88:89]
	v_pk_mul_f32 v[68:69], v[76:77], v[68:69]
	v_cvt_pk_bf16_f32 v83, v88, v89
	global_store_dwordx4 v[98:99], v[82:85], off nt
	v_exp_f32_e32 v88, v80
	v_exp_f32_e32 v89, v81
	v_exp_f32_e32 v84, v78
	v_exp_f32_e32 v85, v79
	v_pk_add_f32 v[90:91], v[90:91], 1.0 op_sel_hi:[1,0]
	v_pk_add_f32 v[86:87], v[86:87], 1.0 op_sel_hi:[1,0]
	v_rcp_f32_e32 v90, v90
	v_pk_add_f32 v[84:85], v[84:85], 1.0 op_sel_hi:[1,0]
	v_rcp_f32_e32 v86, v86
	v_rcp_f32_e32 v87, v87
	v_rcp_f32_e32 v91, v91
	v_or_b32_e32 v82, 48, v136
	v_pk_add_f32 v[88:89], v[88:89], 1.0 op_sel_hi:[1,0]
	v_rcp_f32_e32 v84, v84
	v_rcp_f32_e32 v85, v85
	v_ashrrev_i32_e32 v83, 31, v82
	v_rcp_f32_e32 v88, v88
	v_rcp_f32_e32 v89, v89
	v_lshl_add_u64 v[82:83], s[16:17], 0, v[82:83]
	v_pk_mul_f32 v[66:67], v[74:75], v[66:67]
	v_lshlrev_b64 v[82:83], 7, v[82:83]
	v_pk_mul_f32 v[70:71], v[78:79], v[70:71]
	v_pk_mul_f32 v[74:75], v[90:91], v[68:69]
	v_pk_mul_f32 v[68:69], v[86:87], v[66:67]
	v_lshl_add_u64 v[82:83], v[130:131], 0, v[82:83]
	v_pk_mul_f32 v[72:73], v[80:81], v[72:73]
	v_pk_mul_f32 v[70:71], v[84:85], v[70:71]
	v_cvt_pk_bf16_f32 v68, v68, v69
	v_cvt_pk_bf16_f32 v69, v74, v75
	v_pk_mul_f32 v[72:73], v[88:89], v[72:73]
	v_cvt_pk_bf16_f32 v66, v70, v71
	v_exp_f32_e32 v70, v58
	v_cvt_pk_bf16_f32 v67, v72, v73
	global_store_dwordx4 v[82:83], v[66:69], off nt
	v_exp_f32_e32 v74, v60
	v_exp_f32_e32 v75, v61
	v_exp_f32_e32 v68, v62
	v_exp_f32_e32 v69, v63
	v_exp_f32_e32 v71, v59
	v_exp_f32_e32 v72, v64
	v_exp_f32_e32 v73, v65
	v_pk_add_f32 v[68:69], v[68:69], 1.0 op_sel_hi:[1,0]
	v_pk_add_f32 v[74:75], v[74:75], 1.0 op_sel_hi:[1,0]
	v_pk_add_f32 v[70:71], v[70:71], 1.0 op_sel_hi:[1,0]
	v_rcp_f32_e32 v68, v68
	v_rcp_f32_e32 v70, v70
	v_rcp_f32_e32 v69, v69
	v_rcp_f32_e32 v71, v71
	v_rcp_f32_e32 v74, v74
	v_rcp_f32_e32 v75, v75
	v_add_u32_e32 v66, 0x80, v136
	v_pk_add_f32 v[72:73], v[72:73], 1.0 op_sel_hi:[1,0]
	v_ashrrev_i32_e32 v67, 31, v66
	v_rcp_f32_e32 v72, v72
	v_rcp_f32_e32 v73, v73
	v_lshl_add_u64 v[66:67], s[16:17], 0, v[66:67]
	v_pk_mul_f32 v[54:55], v[62:63], v[54:55]
	v_pk_mul_f32 v[52:53], v[60:61], v[52:53]
	v_pk_mul_f32 v[50:51], v[58:59], v[50:51]
	v_lshlrev_b64 v[66:67], 7, v[66:67]
	v_pk_mul_f32 v[54:55], v[68:69], v[54:55]
	v_pk_mul_f32 v[58:59], v[74:75], v[52:53]
	v_pk_mul_f32 v[52:53], v[70:71], v[50:51]
	v_lshl_add_u64 v[66:67], v[130:131], 0, v[66:67]
	v_pk_mul_f32 v[56:57], v[64:65], v[56:57]
	v_cvt_pk_bf16_f32 v50, v54, v55
	v_cvt_pk_bf16_f32 v52, v52, v53
	v_cvt_pk_bf16_f32 v53, v58, v59
	v_exp_f32_e32 v54, v42
	v_exp_f32_e32 v58, v44
	v_exp_f32_e32 v59, v45
	v_exp_f32_e32 v55, v43
	v_pk_mul_f32 v[56:57], v[72:73], v[56:57]
	v_pk_mul_f32 v[36:37], v[44:45], v[36:37]
	v_cvt_pk_bf16_f32 v51, v56, v57
	global_store_dwordx4 v[66:67], v[50:53], off nt
	v_exp_f32_e32 v56, v48
	v_exp_f32_e32 v57, v49
	v_exp_f32_e32 v52, v46
	v_exp_f32_e32 v53, v47
	v_pk_add_f32 v[58:59], v[58:59], 1.0 op_sel_hi:[1,0]
	v_pk_add_f32 v[54:55], v[54:55], 1.0 op_sel_hi:[1,0]
	v_rcp_f32_e32 v58, v58
	v_pk_add_f32 v[52:53], v[52:53], 1.0 op_sel_hi:[1,0]
	v_rcp_f32_e32 v54, v54
	v_rcp_f32_e32 v55, v55
	v_rcp_f32_e32 v59, v59
	v_add_u32_e32 v50, 0x90, v136
	v_pk_add_f32 v[56:57], v[56:57], 1.0 op_sel_hi:[1,0]
	v_rcp_f32_e32 v52, v52
	v_rcp_f32_e32 v53, v53
	v_ashrrev_i32_e32 v51, 31, v50
	v_rcp_f32_e32 v56, v56
	v_rcp_f32_e32 v57, v57
	v_lshl_add_u64 v[50:51], s[16:17], 0, v[50:51]
	v_pk_mul_f32 v[34:35], v[42:43], v[34:35]
	v_lshlrev_b64 v[50:51], 7, v[50:51]
	v_pk_mul_f32 v[38:39], v[46:47], v[38:39]
	v_pk_mul_f32 v[42:43], v[58:59], v[36:37]
	v_pk_mul_f32 v[36:37], v[54:55], v[34:35]
	v_lshl_add_u64 v[50:51], v[130:131], 0, v[50:51]
	v_pk_mul_f32 v[40:41], v[48:49], v[40:41]
	v_pk_mul_f32 v[38:39], v[52:53], v[38:39]
	v_cvt_pk_bf16_f32 v36, v36, v37
	v_cvt_pk_bf16_f32 v37, v42, v43
	v_pk_mul_f32 v[40:41], v[56:57], v[40:41]
	v_cvt_pk_bf16_f32 v34, v38, v39
	v_exp_f32_e32 v38, v26
	v_cvt_pk_bf16_f32 v35, v40, v41
	global_store_dwordx4 v[50:51], v[34:37], off nt
	v_exp_f32_e32 v42, v28
	v_exp_f32_e32 v43, v29
	v_exp_f32_e32 v36, v30
	v_exp_f32_e32 v37, v31
	v_exp_f32_e32 v39, v27
	v_exp_f32_e32 v40, v32
	v_exp_f32_e32 v41, v33
	v_pk_add_f32 v[36:37], v[36:37], 1.0 op_sel_hi:[1,0]
	v_pk_add_f32 v[42:43], v[42:43], 1.0 op_sel_hi:[1,0]
	v_pk_add_f32 v[38:39], v[38:39], 1.0 op_sel_hi:[1,0]
	v_pk_add_f32 v[40:41], v[40:41], 1.0 op_sel_hi:[1,0]
	v_rcp_f32_e32 v36, v36
	v_rcp_f32_e32 v38, v38
	v_rcp_f32_e32 v37, v37
	v_rcp_f32_e32 v39, v39
	v_rcp_f32_e32 v42, v42
	v_rcp_f32_e32 v43, v43
	v_add_u32_e32 v34, 0xa0, v136
	v_rcp_f32_e32 v40, v40
	v_rcp_f32_e32 v41, v41
	v_ashrrev_i32_e32 v35, 31, v34
	v_lshl_add_u64 v[34:35], s[16:17], 0, v[34:35]
	v_pk_mul_f32 v[22:23], v[30:31], v[22:23]
	v_pk_mul_f32 v[20:21], v[28:29], v[20:21]
	v_pk_mul_f32 v[18:19], v[26:27], v[18:19]
	v_lshlrev_b64 v[34:35], 7, v[34:35]
	v_pk_mul_f32 v[24:25], v[32:33], v[24:25]
	v_pk_mul_f32 v[22:23], v[36:37], v[22:23]
	v_pk_mul_f32 v[26:27], v[42:43], v[20:21]
	v_pk_mul_f32 v[20:21], v[38:39], v[18:19]
	v_lshl_add_u64 v[34:35], v[130:131], 0, v[34:35]
	v_pk_mul_f32 v[24:25], v[40:41], v[24:25]
	v_cvt_pk_bf16_f32 v18, v22, v23
	v_cvt_pk_bf16_f32 v20, v20, v21
	v_cvt_pk_bf16_f32 v21, v26, v27
	v_exp_f32_e32 v22, v10
	v_exp_f32_e32 v26, v12
	v_exp_f32_e32 v27, v13
	v_exp_f32_e32 v23, v11
	v_cvt_pk_bf16_f32 v19, v24, v25
	global_store_dwordx4 v[34:35], v[18:21], off nt
	v_exp_f32_e32 v24, v16
	v_exp_f32_e32 v25, v17
	v_exp_f32_e32 v20, v14
	v_exp_f32_e32 v21, v15
	v_pk_add_f32 v[26:27], v[26:27], 1.0 op_sel_hi:[1,0]
	v_pk_add_f32 v[22:23], v[22:23], 1.0 op_sel_hi:[1,0]
	v_add_u32_e32 v18, 0xb0, v136
	v_pk_add_f32 v[24:25], v[24:25], 1.0 op_sel_hi:[1,0]
	v_pk_add_f32 v[20:21], v[20:21], 1.0 op_sel_hi:[1,0]
	v_rcp_f32_e32 v22, v22
	v_rcp_f32_e32 v23, v23
	v_rcp_f32_e32 v26, v26
	v_rcp_f32_e32 v27, v27
	v_ashrrev_i32_e32 v19, 31, v18
	v_rcp_f32_e32 v20, v20
	v_rcp_f32_e32 v21, v21
	v_rcp_f32_e32 v24, v24
	v_rcp_f32_e32 v25, v25
	v_lshl_add_u64 v[18:19], s[16:17], 0, v[18:19]
	v_lshlrev_b64 v[18:19], 7, v[18:19]
	v_pk_mul_f32 v[4:5], v[12:13], v[4:5]
	v_pk_mul_f32 v[2:3], v[10:11], v[2:3]
	v_lshl_add_u64 v[18:19], v[130:131], 0, v[18:19]
	v_pk_mul_f32 v[8:9], v[16:17], v[8:9]
	v_pk_mul_f32 v[6:7], v[14:15], v[6:7]
	v_pk_mul_f32 v[10:11], v[26:27], v[4:5]
	v_pk_mul_f32 v[4:5], v[22:23], v[2:3]
	s_andn2_b64 vcc, exec, s[2:3]
	s_mov_b64 s[2:3], -1
	v_pk_mul_f32 v[8:9], v[24:25], v[8:9]
	v_pk_mul_f32 v[6:7], v[20:21], v[6:7]
	v_cvt_pk_bf16_f32 v3, v8, v9
	v_cvt_pk_bf16_f32 v4, v4, v5
	v_cvt_pk_bf16_f32 v5, v10, v11
	s_nop 0
	v_cvt_pk_bf16_f32 v2, v6, v7
	global_store_dwordx4 v[18:19], v[2:5], off nt
	s_cbranch_vccnz .LBB0_2590
	s_andn2_b64 vcc, exec, s[4:5]
	s_cbranch_vccnz .LBB0_2589
	s_barrier
	s_branch .LBB0_2589
